# LDS-staged epilogues: no wait between the tile's ds_write and ds_read (same-wave LDS ops execute in order)
# baseline (speedup 1.0000x reference)
.LBB0_95:
	v_div_scale_f32 v35, s[0:1], v34, v34, 1.0
	v_rcp_f32_e32 v36, v35
	v_div_scale_f32 v37, vcc, 1.0, v34, 1.0
	v_mov_b32_e32 v149, v99
	v_fma_f32 v38, -v35, v36, 1.0
	v_fmac_f32_e32 v36, v38, v36
	v_mul_f32_e32 v38, v37, v36
	v_fma_f32 v39, -v35, v38, v37
	v_fmac_f32_e32 v38, v39, v36
	v_fma_f32 v35, -v35, v38, v37
	v_div_fmas_f32 v35, v35, v36, v38
	v_div_fixup_f32 v34, v35, v34, 1.0
	s_waitcnt vmcnt(0) lgkmcnt(0)
	v_pk_mul_f32 v[0:1], v[34:35], v[0:1] op_sel_hi:[0,1]
	v_pk_mul_f32 v[2:3], v[34:35], v[2:3] op_sel_hi:[0,1]
	v_pk_mul_f32 v[4:5], v[34:35], v[4:5] op_sel_hi:[0,1]
	v_pk_mul_f32 v[6:7], v[34:35], v[6:7] op_sel_hi:[0,1]
	v_pk_mul_f32 v[8:9], v[34:35], v[8:9] op_sel_hi:[0,1]
	v_pk_mul_f32 v[10:11], v[34:35], v[10:11] op_sel_hi:[0,1]
	v_pk_mul_f32 v[12:13], v[34:35], v[12:13] op_sel_hi:[0,1]
	v_pk_mul_f32 v[14:15], v[34:35], v[14:15] op_sel_hi:[0,1]
	v_pk_mul_f32 v[16:17], v[34:35], v[16:17] op_sel_hi:[0,1]
	v_pk_mul_f32 v[18:19], v[34:35], v[18:19] op_sel_hi:[0,1]
	v_pk_mul_f32 v[20:21], v[34:35], v[20:21] op_sel_hi:[0,1]
	v_pk_mul_f32 v[22:23], v[34:35], v[22:23] op_sel_hi:[0,1]
	v_pk_mul_f32 v[24:25], v[34:35], v[24:25] op_sel_hi:[0,1]
	v_pk_mul_f32 v[26:27], v[34:35], v[26:27] op_sel_hi:[0,1]
	v_pk_mul_f32 v[28:29], v[34:35], v[28:29] op_sel_hi:[0,1]
	v_pk_mul_f32 v[30:31], v[34:35], v[30:31] op_sel_hi:[0,1]
	v_cvt_pk_bf16_f32 v16, v16, v17
	v_cvt_pk_bf16_f32 v17, v18, v19
	v_cvt_pk_bf16_f32 v18, v20, v21
	v_cvt_pk_bf16_f32 v19, v22, v23
	v_cvt_pk_bf16_f32 v20, v24, v25
	v_cvt_pk_bf16_f32 v21, v26, v27
	v_cvt_pk_bf16_f32 v22, v28, v29
	v_cvt_pk_bf16_f32 v23, v30, v31
	v_cvt_pk_bf16_f32 v0, v0, v1
	v_cvt_pk_bf16_f32 v1, v2, v3
	v_cvt_pk_bf16_f32 v2, v4, v5
	v_cvt_pk_bf16_f32 v3, v6, v7
	v_cvt_pk_bf16_f32 v4, v8, v9
	v_cvt_pk_bf16_f32 v5, v10, v11
	v_cvt_pk_bf16_f32 v6, v12, v13
	v_cvt_pk_bf16_f32 v7, v14, v15
	v_and_b32_e32 v38, 63, v186
	v_lshrrev_b32_e32 v39, 6, v186
	v_lshlrev_b32_e32 v39, 11, v39
	v_add_u32_e32 v39, 0x20100, v39
	v_lshl_add_u32 v35, v38, 4, v39
	v_and_b32_e32 v34, 15, v38
	v_lshl_add_u32 v34, v34, 7, v39
	v_lshrrev_b32_e32 v36, 5, v38
	v_lshl_add_u32 v34, v36, 3, v34
	v_lshrrev_b32_e32 v36, 3, v38
	v_lshlrev_b32_e32 v36, 11, v36
	v_and_b32_e32 v37, 7, v38
	v_lshl_add_u32 v36, v37, 4, v36
	v_add_u32_e32 v37, 0x4000, v36
	s_add_i32 s14, s14, s3
	s_add_i32 s13, s13, s3
	s_mov_b32 s0, 0x0000ffff
	s_mov_b32 s1, 0x0000ffff
	s_mov_b64 exec, s[0:1]
	ds_write_b64 v34, v[16:17] offset:0
	ds_write_b64 v34, v[0:1] offset:64
	ds_write_b64 v34, v[18:19] offset:16
	ds_write_b64 v34, v[2:3] offset:80
	ds_write_b64 v34, v[20:21] offset:32
	ds_write_b64 v34, v[4:5] offset:96
	ds_write_b64 v34, v[22:23] offset:48
	ds_write_b64 v34, v[6:7] offset:112
	s_mov_b64 exec, -1
	v_readlane_b32 s0, v32, 0
	v_readlane_b32 s1, v33, 0
	ds_read_b128 v[24:27], v35
	ds_read_b128 v[28:31], v35 offset:1024
	s_nop 1
	s_waitcnt lgkmcnt(0)
	global_store_dwordx4 v36, v[24:27], s[0:1]
	global_store_dwordx4 v37, v[28:31], s[0:1]
	s_mov_b32 s0, 0xffff0000
	s_mov_b32 s1, 0xffff0000
	s_mov_b64 exec, s[0:1]
	ds_write_b64 v34, v[16:17] offset:0
	ds_write_b64 v34, v[0:1] offset:64
	ds_write_b64 v34, v[18:19] offset:16
	ds_write_b64 v34, v[2:3] offset:80
	ds_write_b64 v34, v[20:21] offset:32
	ds_write_b64 v34, v[4:5] offset:96
	ds_write_b64 v34, v[22:23] offset:48
	ds_write_b64 v34, v[6:7] offset:112
	s_mov_b64 exec, -1
	v_readlane_b32 s0, v32, 16
	v_readlane_b32 s1, v33, 16
	ds_read_b128 v[8:11], v35
	ds_read_b128 v[12:15], v35 offset:1024
	s_nop 1
	s_waitcnt lgkmcnt(0)
	global_store_dwordx4 v36, v[8:11], s[0:1]
	global_store_dwordx4 v37, v[12:15], s[0:1]
	s_cmp_ge_i32 s14, s21
	s_cbranch_scc1 .LBB0_599

.LBB0_874:
	s_cmpk_gt_i32 s56, 0x7f
	s_cbranch_scc1 .Lresid_orig
	s_and_b64 vcc, exec, s[10:11]
	s_cbranch_vccz .Lresid_nonorm
	v_readlane_b32 s62, v252, 7
	v_readlane_b32 s63, v252, 8
	s_lshr_b32 s20, s56, 4
	s_mul_i32 s20, s20, 0x6000
	s_add_u32 s44, s66, s20
	s_addc_u32 s45, s12, 0
	s_add_u32 s46, s13, s20
	s_addc_u32 s47, s26, 0
	s_mov_b32 s60, s38
	s_mov_b32 s61, s95
	v_lshl_or_b32 v236, s57, 8, v246
	v_lshl_add_u32 v237, s56, 8, v244
	v_lshlrev_b32_e32 v210, 2, v236
	v_lshl_add_u32 v211, v237, 12, v210
	v_and_b32_e32 v212, 4, v246
	v_mul_u32_u24_e32 v212, 6, v212
	v_lshl_add_u32 v212, v236, 1, v212
	v_lshl_add_u32 v212, v237, 11, v212
	v_lshlrev_b32_e32 v213, 2, v237
	v_lshlrev_b32_e32 v214, 2, v231
	v_lshlrev_b32_e32 v215, 2, v232
	v_and_b32_e32 v228, 63, v186
	v_lshrrev_b32_e32 v229, 6, v186
	v_lshlrev_b32_e32 v229, 11, v229
	v_add_u32_e32 v229, 0x20100, v229
	v_lshl_add_u32 v237, v228, 4, v229
	v_and_b32_e32 v236, 15, v244
	v_lshl_add_u32 v236, v236, 7, v229
	v_and_b32_e32 v229, 12, v246
	v_lshl_add_u32 v236, v229, 2, v236
	v_lshrrev_b32_e32 v214, 3, v228
	v_and_b32_e32 v229, 64, v244
	v_add_u32_e32 v214, v214, v229
	v_lshl_add_u32 v214, s56, 8, v214
	v_and_b32_e32 v228, 7, v228
	v_lshlrev_b32_e32 v228, 2, v228
	v_and_b32_e32 v229, 0x60, v246
	v_add_u32_e32 v228, v228, v229
	v_lshl_add_u32 v228, s57, 8, v228
	v_lshlrev_b32_e32 v228, 2, v228
	v_lshl_add_u32 v214, v214, 12, v228
	v_add_u32_e32 v215, 0x8000, v214
	global_load_dwordx4 v[60:63], v210, s[44:45] offset:0
	global_load_dwordx4 v[64:67], v210, s[44:45] offset:64
	global_load_dwordx4 v[68:71], v210, s[44:45] offset:512
	global_load_dwordx4 v[72:75], v210, s[44:45] offset:576
	global_load_dwordx4 v[148:151], v210, s[46:47] offset:0
	global_load_dwordx4 v[152:155], v210, s[46:47] offset:64
	global_load_dwordx4 v[156:159], v210, s[46:47] offset:512
	global_load_dwordx4 v[160:163], v210, s[46:47] offset:576
	global_load_dwordx4 v[194:197], v210, s[8:9] offset:0
	global_load_dwordx4 v[198:201], v210, s[8:9] offset:64
	global_load_dwordx4 v[202:205], v210, s[8:9] offset:512
	global_load_dwordx4 v[206:209], v210, s[8:9] offset:576
	s_mov_b32 s72, s60
	s_mov_b32 s73, s61
	global_load_dwordx4 v[164:167], v211, s[72:73] offset:0
	global_load_dwordx4 v[168:171], v211, s[72:73] offset:64
	global_load_dwordx4 v[172:175], v211, s[72:73] offset:512
	global_load_dwordx4 v[176:179], v211, s[72:73] offset:576
	s_waitcnt vmcnt(4)
	v_pk_add_f32 v[148:149], v[148:149], 1.0 op_sel_hi:[1,0]
	v_pk_add_f32 v[150:151], v[150:151], 1.0 op_sel_hi:[1,0]
	v_pk_mul_f32 v[148:149], v[194:195], v[148:149]
	v_pk_mul_f32 v[150:151], v[196:197], v[150:151]
	v_pk_add_f32 v[152:153], v[152:153], 1.0 op_sel_hi:[1,0]
	v_pk_add_f32 v[154:155], v[154:155], 1.0 op_sel_hi:[1,0]
	v_pk_mul_f32 v[152:153], v[198:199], v[152:153]
	v_pk_mul_f32 v[154:155], v[200:201], v[154:155]
	v_pk_add_f32 v[156:157], v[156:157], 1.0 op_sel_hi:[1,0]
	v_pk_add_f32 v[158:159], v[158:159], 1.0 op_sel_hi:[1,0]
	v_pk_mul_f32 v[156:157], v[202:203], v[156:157]
	v_pk_mul_f32 v[158:159], v[204:205], v[158:159]
	v_pk_add_f32 v[160:161], v[160:161], 1.0 op_sel_hi:[1,0]
	v_pk_add_f32 v[162:163], v[162:163], 1.0 op_sel_hi:[1,0]
	v_pk_mul_f32 v[160:161], v[206:207], v[160:161]
	v_pk_mul_f32 v[162:163], v[208:209], v[162:163]
	s_add_u32 s72, s60, 0x10000
	s_addc_u32 s73, s61, 0
	global_load_dwordx4 v[194:197], v211, s[72:73] offset:0
	global_load_dwordx4 v[198:201], v211, s[72:73] offset:64
	global_load_dwordx4 v[202:205], v211, s[72:73] offset:512
	global_load_dwordx4 v[206:209], v211, s[72:73] offset:576
	v_mov_b32_e32 v216, 0
	v_mov_b32_e32 v217, 0
	v_mov_b32_e32 v218, 0
	v_mov_b32_e32 v219, 0
	v_mov_b32_e32 v228, 0
	v_mov_b32_e32 v229, 0
	v_mov_b32_e32 v234, 0
	v_mov_b32_e32 v235, 0
	s_waitcnt vmcnt(4)
	s_mov_b32 s74, s62
	s_mov_b32 s75, s63
	s_mov_b32 s76, s88
	s_mov_b32 s77, s89
	v_pk_fma_f32 v[164:165], v[144:145], v[60:61], v[164:165]
	v_pk_fma_f32 v[166:167], v[146:147], v[62:63], v[166:167]
	v_pk_fma_f32 v[168:169], v[140:141], v[64:65], v[168:169]
	v_pk_fma_f32 v[170:171], v[142:143], v[66:67], v[170:171]
	ds_write_b128 v236, v[164:167]
	ds_write_b128 v236, v[168:171] offset:64
	v_fmac_f32_e32 v216, v164, v164
	v_fmac_f32_e32 v216, v165, v165
	v_fmac_f32_e32 v216, v166, v166
	v_fmac_f32_e32 v216, v167, v167
	v_pk_mul_f32 v[144:145], v[148:149], v[164:165]
	v_pk_mul_f32 v[146:147], v[150:151], v[166:167]
	v_fmac_f32_e32 v216, v168, v168
	v_fmac_f32_e32 v216, v169, v169
	v_fmac_f32_e32 v216, v170, v170
	v_fmac_f32_e32 v216, v171, v171
	v_pk_mul_f32 v[140:141], v[152:153], v[168:169]
	v_pk_mul_f32 v[142:143], v[154:155], v[170:171]
	ds_read_b128 v[164:167], v237
	ds_read_b128 v[168:171], v237 offset:1024
	v_cvt_pk_bf16_f32 v144, v144, v145
	v_cvt_pk_bf16_f32 v145, v146, v147
	v_cvt_pk_bf16_f32 v146, v140, v141
	v_cvt_pk_bf16_f32 v147, v142, v143
	s_nop 1
	v_permlane16_swap_b32 v144, v146
	v_permlane16_swap_b32 v145, v147
	global_store_dwordx4 v212, v[144:147], s[76:77] offset:0
	s_waitcnt lgkmcnt(0)
	global_store_dwordx4 v214, v[164:167], s[74:75] offset:0
	global_store_dwordx4 v215, v[168:171], s[74:75] offset:0
	v_pk_fma_f32 v[172:173], v[136:137], v[68:69], v[172:173]
	v_pk_fma_f32 v[174:175], v[138:139], v[70:71], v[174:175]
	v_pk_fma_f32 v[176:177], v[132:133], v[72:73], v[176:177]
	v_pk_fma_f32 v[178:179], v[134:135], v[74:75], v[178:179]
	ds_write_b128 v236, v[172:175]
	ds_write_b128 v236, v[176:179] offset:64
	v_fmac_f32_e32 v216, v172, v172
	v_fmac_f32_e32 v216, v173, v173
	v_fmac_f32_e32 v216, v174, v174
	v_fmac_f32_e32 v216, v175, v175
	v_pk_mul_f32 v[136:137], v[156:157], v[172:173]
	v_pk_mul_f32 v[138:139], v[158:159], v[174:175]
	v_fmac_f32_e32 v216, v176, v176
	v_fmac_f32_e32 v216, v177, v177
	v_fmac_f32_e32 v216, v178, v178
	v_fmac_f32_e32 v216, v179, v179
	v_pk_mul_f32 v[132:133], v[160:161], v[176:177]
	v_pk_mul_f32 v[134:135], v[162:163], v[178:179]
	ds_read_b128 v[172:175], v237
	ds_read_b128 v[176:179], v237 offset:1024
	v_cvt_pk_bf16_f32 v136, v136, v137
	v_cvt_pk_bf16_f32 v137, v138, v139
	v_cvt_pk_bf16_f32 v138, v132, v133
	v_cvt_pk_bf16_f32 v139, v134, v135
	s_nop 1
	v_permlane16_swap_b32 v136, v138
	v_permlane16_swap_b32 v137, v139
	global_store_dwordx4 v212, v[136:139], s[76:77] offset:256
	s_waitcnt lgkmcnt(0)
	global_store_dwordx4 v214, v[172:175], s[74:75] offset:512
	global_store_dwordx4 v215, v[176:179], s[74:75] offset:512
	s_add_u32 s72, s60, 0x20000
	s_addc_u32 s73, s61, 0
	global_load_dwordx4 v[164:167], v211, s[72:73] offset:0
	global_load_dwordx4 v[168:171], v211, s[72:73] offset:64
	global_load_dwordx4 v[172:175], v211, s[72:73] offset:512
	global_load_dwordx4 v[176:179], v211, s[72:73] offset:576
	s_add_u32 s72, s60, 0x30000
	s_addc_u32 s73, s61, 0
	global_load_dwordx4 v[144:147], v211, s[72:73] offset:0
	global_load_dwordx4 v[140:143], v211, s[72:73] offset:64
	global_load_dwordx4 v[136:139], v211, s[72:73] offset:512
	global_load_dwordx4 v[132:135], v211, s[72:73] offset:576
	s_waitcnt vmcnt(14)
	s_add_u32 s74, s62, 0x10000
	s_addc_u32 s75, s63, 0
	s_add_u32 s76, s88, 0x8000
	s_addc_u32 s77, s89, 0
	v_pk_fma_f32 v[194:195], v[128:129], v[60:61], v[194:195]
	v_pk_fma_f32 v[196:197], v[130:131], v[62:63], v[196:197]
	v_pk_fma_f32 v[198:199], v[124:125], v[64:65], v[198:199]
	v_pk_fma_f32 v[200:201], v[126:127], v[66:67], v[200:201]
	ds_write_b128 v236, v[194:197]
	ds_write_b128 v236, v[198:201] offset:64
	v_fmac_f32_e32 v217, v194, v194
	v_fmac_f32_e32 v217, v195, v195
	v_fmac_f32_e32 v217, v196, v196
	v_fmac_f32_e32 v217, v197, v197
	v_pk_mul_f32 v[128:129], v[148:149], v[194:195]
	v_pk_mul_f32 v[130:131], v[150:151], v[196:197]
	v_fmac_f32_e32 v217, v198, v198
	v_fmac_f32_e32 v217, v199, v199
	v_fmac_f32_e32 v217, v200, v200
	v_fmac_f32_e32 v217, v201, v201
	v_pk_mul_f32 v[124:125], v[152:153], v[198:199]
	v_pk_mul_f32 v[126:127], v[154:155], v[200:201]
	ds_read_b128 v[194:197], v237
	ds_read_b128 v[198:201], v237 offset:1024
	v_cvt_pk_bf16_f32 v128, v128, v129
	v_cvt_pk_bf16_f32 v129, v130, v131
	v_cvt_pk_bf16_f32 v130, v124, v125
	v_cvt_pk_bf16_f32 v131, v126, v127
	s_nop 1
	v_permlane16_swap_b32 v128, v130
	v_permlane16_swap_b32 v129, v131
	global_store_dwordx4 v212, v[128:131], s[76:77] offset:0
	s_waitcnt lgkmcnt(0)
	global_store_dwordx4 v214, v[194:197], s[74:75] offset:0
	global_store_dwordx4 v215, v[198:201], s[74:75] offset:0
	v_pk_fma_f32 v[202:203], v[120:121], v[68:69], v[202:203]
	v_pk_fma_f32 v[204:205], v[122:123], v[70:71], v[204:205]
	v_pk_fma_f32 v[206:207], v[116:117], v[72:73], v[206:207]
	v_pk_fma_f32 v[208:209], v[118:119], v[74:75], v[208:209]
	ds_write_b128 v236, v[202:205]
	ds_write_b128 v236, v[206:209] offset:64
	v_fmac_f32_e32 v217, v202, v202
	v_fmac_f32_e32 v217, v203, v203
	v_fmac_f32_e32 v217, v204, v204
	v_fmac_f32_e32 v217, v205, v205
	v_pk_mul_f32 v[120:121], v[156:157], v[202:203]
	v_pk_mul_f32 v[122:123], v[158:159], v[204:205]
	v_fmac_f32_e32 v217, v206, v206
	v_fmac_f32_e32 v217, v207, v207
	v_fmac_f32_e32 v217, v208, v208
	v_fmac_f32_e32 v217, v209, v209
	v_pk_mul_f32 v[116:117], v[160:161], v[206:207]
	v_pk_mul_f32 v[118:119], v[162:163], v[208:209]
	ds_read_b128 v[202:205], v237
	ds_read_b128 v[206:209], v237 offset:1024
	v_cvt_pk_bf16_f32 v120, v120, v121
	v_cvt_pk_bf16_f32 v121, v122, v123
	v_cvt_pk_bf16_f32 v122, v116, v117
	v_cvt_pk_bf16_f32 v123, v118, v119
	s_nop 1
	v_permlane16_swap_b32 v120, v122
	v_permlane16_swap_b32 v121, v123
	global_store_dwordx4 v212, v[120:123], s[76:77] offset:256
	s_waitcnt lgkmcnt(0)
	global_store_dwordx4 v214, v[202:205], s[74:75] offset:512
	global_store_dwordx4 v215, v[206:209], s[74:75] offset:512
	s_add_u32 s72, s60, 0x80000
	s_addc_u32 s73, s61, 0
	global_load_dwordx4 v[194:197], v211, s[72:73] offset:0
	global_load_dwordx4 v[198:201], v211, s[72:73] offset:64
	global_load_dwordx4 v[202:205], v211, s[72:73] offset:512
	global_load_dwordx4 v[206:209], v211, s[72:73] offset:576
	s_add_u32 s72, s60, 0x90000
	s_addc_u32 s73, s61, 0
	global_load_dwordx4 v[128:131], v211, s[72:73] offset:0
	global_load_dwordx4 v[124:127], v211, s[72:73] offset:64
	global_load_dwordx4 v[120:123], v211, s[72:73] offset:512
	global_load_dwordx4 v[116:119], v211, s[72:73] offset:576
	s_waitcnt vmcnt(18)
	s_add_u32 s74, s62, 0x20000
	s_addc_u32 s75, s63, 0
	s_add_u32 s76, s88, 0x10000
	s_addc_u32 s77, s89, 0
	v_pk_fma_f32 v[164:165], v[112:113], v[60:61], v[164:165]
	v_pk_fma_f32 v[166:167], v[114:115], v[62:63], v[166:167]
	v_pk_fma_f32 v[168:169], v[108:109], v[64:65], v[168:169]
	v_pk_fma_f32 v[170:171], v[110:111], v[66:67], v[170:171]
	ds_write_b128 v236, v[164:167]
	ds_write_b128 v236, v[168:171] offset:64
	v_fmac_f32_e32 v218, v164, v164
	v_fmac_f32_e32 v218, v165, v165
	v_fmac_f32_e32 v218, v166, v166
	v_fmac_f32_e32 v218, v167, v167
	v_pk_mul_f32 v[112:113], v[148:149], v[164:165]
	v_pk_mul_f32 v[114:115], v[150:151], v[166:167]
	v_fmac_f32_e32 v218, v168, v168
	v_fmac_f32_e32 v218, v169, v169
	v_fmac_f32_e32 v218, v170, v170
	v_fmac_f32_e32 v218, v171, v171
	v_pk_mul_f32 v[108:109], v[152:153], v[168:169]
	v_pk_mul_f32 v[110:111], v[154:155], v[170:171]
	ds_read_b128 v[164:167], v237
	ds_read_b128 v[168:171], v237 offset:1024
	v_cvt_pk_bf16_f32 v112, v112, v113
	v_cvt_pk_bf16_f32 v113, v114, v115
	v_cvt_pk_bf16_f32 v114, v108, v109
	v_cvt_pk_bf16_f32 v115, v110, v111
	s_nop 1
	v_permlane16_swap_b32 v112, v114
	v_permlane16_swap_b32 v113, v115
	global_store_dwordx4 v212, v[112:115], s[76:77] offset:0
	s_waitcnt lgkmcnt(0)
	global_store_dwordx4 v214, v[164:167], s[74:75] offset:0
	global_store_dwordx4 v215, v[168:171], s[74:75] offset:0
	v_pk_fma_f32 v[172:173], v[104:105], v[68:69], v[172:173]
	v_pk_fma_f32 v[174:175], v[106:107], v[70:71], v[174:175]
	v_pk_fma_f32 v[176:177], v[100:101], v[72:73], v[176:177]
	v_pk_fma_f32 v[178:179], v[102:103], v[74:75], v[178:179]
	ds_write_b128 v236, v[172:175]
	ds_write_b128 v236, v[176:179] offset:64
	v_fmac_f32_e32 v218, v172, v172
	v_fmac_f32_e32 v218, v173, v173
	v_fmac_f32_e32 v218, v174, v174
	v_fmac_f32_e32 v218, v175, v175
	v_pk_mul_f32 v[104:105], v[156:157], v[172:173]
	v_pk_mul_f32 v[106:107], v[158:159], v[174:175]
	v_fmac_f32_e32 v218, v176, v176
	v_fmac_f32_e32 v218, v177, v177
	v_fmac_f32_e32 v218, v178, v178
	v_fmac_f32_e32 v218, v179, v179
	v_pk_mul_f32 v[100:101], v[160:161], v[176:177]
	v_pk_mul_f32 v[102:103], v[162:163], v[178:179]
	ds_read_b128 v[172:175], v237
	ds_read_b128 v[176:179], v237 offset:1024
	v_cvt_pk_bf16_f32 v104, v104, v105
	v_cvt_pk_bf16_f32 v105, v106, v107
	v_cvt_pk_bf16_f32 v106, v100, v101
	v_cvt_pk_bf16_f32 v107, v102, v103
	s_nop 1
	v_permlane16_swap_b32 v104, v106
	v_permlane16_swap_b32 v105, v107
	global_store_dwordx4 v212, v[104:107], s[76:77] offset:256
	s_waitcnt lgkmcnt(0)
	global_store_dwordx4 v214, v[172:175], s[74:75] offset:512
	global_store_dwordx4 v215, v[176:179], s[74:75] offset:512
	s_add_u32 s72, s60, 0xa0000
	s_addc_u32 s73, s61, 0
	global_load_dwordx4 v[164:167], v211, s[72:73] offset:0
	global_load_dwordx4 v[168:171], v211, s[72:73] offset:64
	global_load_dwordx4 v[172:175], v211, s[72:73] offset:512
	global_load_dwordx4 v[176:179], v211, s[72:73] offset:576
	s_add_u32 s72, s60, 0xb0000
	s_addc_u32 s73, s61, 0
	global_load_dwordx4 v[112:115], v211, s[72:73] offset:0
	global_load_dwordx4 v[108:111], v211, s[72:73] offset:64
	global_load_dwordx4 v[104:107], v211, s[72:73] offset:512
	global_load_dwordx4 v[100:103], v211, s[72:73] offset:576
	s_waitcnt vmcnt(28)
	s_add_u32 s74, s62, 0x30000
	s_addc_u32 s75, s63, 0
	s_add_u32 s76, s88, 0x18000
	s_addc_u32 s77, s89, 0
	v_pk_fma_f32 v[144:145], v[92:93], v[60:61], v[144:145]
	v_pk_fma_f32 v[146:147], v[94:95], v[62:63], v[146:147]
	v_pk_fma_f32 v[140:141], v[88:89], v[64:65], v[140:141]
	v_pk_fma_f32 v[142:143], v[90:91], v[66:67], v[142:143]
	ds_write_b128 v236, v[144:147]
	ds_write_b128 v236, v[140:143] offset:64
	v_fmac_f32_e32 v219, v144, v144
	v_fmac_f32_e32 v219, v145, v145
	v_fmac_f32_e32 v219, v146, v146
	v_fmac_f32_e32 v219, v147, v147
	v_pk_mul_f32 v[92:93], v[148:149], v[144:145]
	v_pk_mul_f32 v[94:95], v[150:151], v[146:147]
	v_fmac_f32_e32 v219, v140, v140
	v_fmac_f32_e32 v219, v141, v141
	v_fmac_f32_e32 v219, v142, v142
	v_fmac_f32_e32 v219, v143, v143
	v_pk_mul_f32 v[88:89], v[152:153], v[140:141]
	v_pk_mul_f32 v[90:91], v[154:155], v[142:143]
	ds_read_b128 v[144:147], v237
	ds_read_b128 v[140:143], v237 offset:1024
	v_cvt_pk_bf16_f32 v92, v92, v93
	v_cvt_pk_bf16_f32 v93, v94, v95
	v_cvt_pk_bf16_f32 v94, v88, v89
	v_cvt_pk_bf16_f32 v95, v90, v91
	s_nop 1
	v_permlane16_swap_b32 v92, v94
	v_permlane16_swap_b32 v93, v95
	global_store_dwordx4 v212, v[92:95], s[76:77] offset:0
	s_waitcnt lgkmcnt(0)
	global_store_dwordx4 v214, v[144:147], s[74:75] offset:0
	global_store_dwordx4 v215, v[140:143], s[74:75] offset:0
	v_pk_fma_f32 v[136:137], v[84:85], v[68:69], v[136:137]
	v_pk_fma_f32 v[138:139], v[86:87], v[70:71], v[138:139]
	v_pk_fma_f32 v[132:133], v[80:81], v[72:73], v[132:133]
	v_pk_fma_f32 v[134:135], v[82:83], v[74:75], v[134:135]
	ds_write_b128 v236, v[136:139]
	ds_write_b128 v236, v[132:135] offset:64
	v_fmac_f32_e32 v219, v136, v136
	v_fmac_f32_e32 v219, v137, v137
	v_fmac_f32_e32 v219, v138, v138
	v_fmac_f32_e32 v219, v139, v139
	v_pk_mul_f32 v[84:85], v[156:157], v[136:137]
	v_pk_mul_f32 v[86:87], v[158:159], v[138:139]
	v_fmac_f32_e32 v219, v132, v132
	v_fmac_f32_e32 v219, v133, v133
	v_fmac_f32_e32 v219, v134, v134
	v_fmac_f32_e32 v219, v135, v135
	v_pk_mul_f32 v[80:81], v[160:161], v[132:133]
	v_pk_mul_f32 v[82:83], v[162:163], v[134:135]
	ds_read_b128 v[136:139], v237
	ds_read_b128 v[132:135], v237 offset:1024
	v_cvt_pk_bf16_f32 v84, v84, v85
	v_cvt_pk_bf16_f32 v85, v86, v87
	v_cvt_pk_bf16_f32 v86, v80, v81
	v_cvt_pk_bf16_f32 v87, v82, v83
	s_nop 1
	v_permlane16_swap_b32 v84, v86
	v_permlane16_swap_b32 v85, v87
	global_store_dwordx4 v212, v[84:87], s[76:77] offset:256
	s_waitcnt lgkmcnt(0)
	global_store_dwordx4 v214, v[136:139], s[74:75] offset:512
	global_store_dwordx4 v215, v[132:135], s[74:75] offset:512
	s_waitcnt vmcnt(24)
	s_add_u32 s74, s62, 0x80000
	s_addc_u32 s75, s63, 0
	s_add_u32 s76, s88, 0x40000
	s_addc_u32 s77, s89, 0
	v_pk_fma_f32 v[194:195], v[76:77], v[60:61], v[194:195]
	v_pk_fma_f32 v[196:197], v[78:79], v[62:63], v[196:197]
	v_pk_fma_f32 v[198:199], v[56:57], v[64:65], v[198:199]
	v_pk_fma_f32 v[200:201], v[58:59], v[66:67], v[200:201]
	ds_write_b128 v236, v[194:197]
	ds_write_b128 v236, v[198:201] offset:64
	v_fmac_f32_e32 v228, v194, v194
	v_fmac_f32_e32 v228, v195, v195
	v_fmac_f32_e32 v228, v196, v196
	v_fmac_f32_e32 v228, v197, v197
	v_pk_mul_f32 v[76:77], v[148:149], v[194:195]
	v_pk_mul_f32 v[78:79], v[150:151], v[196:197]
	v_fmac_f32_e32 v228, v198, v198
	v_fmac_f32_e32 v228, v199, v199
	v_fmac_f32_e32 v228, v200, v200
	v_fmac_f32_e32 v228, v201, v201
	v_pk_mul_f32 v[56:57], v[152:153], v[198:199]
	v_pk_mul_f32 v[58:59], v[154:155], v[200:201]
	ds_read_b128 v[194:197], v237
	ds_read_b128 v[198:201], v237 offset:1024
	v_cvt_pk_bf16_f32 v76, v76, v77
	v_cvt_pk_bf16_f32 v77, v78, v79
	v_cvt_pk_bf16_f32 v78, v56, v57
	v_cvt_pk_bf16_f32 v79, v58, v59
	s_nop 1
	v_permlane16_swap_b32 v76, v78
	v_permlane16_swap_b32 v77, v79
	global_store_dwordx4 v212, v[76:79], s[76:77] offset:0
	s_waitcnt lgkmcnt(0)
	global_store_dwordx4 v214, v[194:197], s[74:75] offset:0
	global_store_dwordx4 v215, v[198:201], s[74:75] offset:0
	v_pk_fma_f32 v[202:203], v[52:53], v[68:69], v[202:203]
	v_pk_fma_f32 v[204:205], v[54:55], v[70:71], v[204:205]
	v_pk_fma_f32 v[206:207], v[48:49], v[72:73], v[206:207]
	v_pk_fma_f32 v[208:209], v[50:51], v[74:75], v[208:209]
	ds_write_b128 v236, v[202:205]
	ds_write_b128 v236, v[206:209] offset:64
	v_fmac_f32_e32 v228, v202, v202
	v_fmac_f32_e32 v228, v203, v203
	v_fmac_f32_e32 v228, v204, v204
	v_fmac_f32_e32 v228, v205, v205
	v_pk_mul_f32 v[52:53], v[156:157], v[202:203]
	v_pk_mul_f32 v[54:55], v[158:159], v[204:205]
	v_fmac_f32_e32 v228, v206, v206
	v_fmac_f32_e32 v228, v207, v207
	v_fmac_f32_e32 v228, v208, v208
	v_fmac_f32_e32 v228, v209, v209
	v_pk_mul_f32 v[48:49], v[160:161], v[206:207]
	v_pk_mul_f32 v[50:51], v[162:163], v[208:209]
	ds_read_b128 v[202:205], v237
	ds_read_b128 v[206:209], v237 offset:1024
	v_cvt_pk_bf16_f32 v52, v52, v53
	v_cvt_pk_bf16_f32 v53, v54, v55
	v_cvt_pk_bf16_f32 v54, v48, v49
	v_cvt_pk_bf16_f32 v55, v50, v51
	s_nop 1
	v_permlane16_swap_b32 v52, v54
	v_permlane16_swap_b32 v53, v55
	global_store_dwordx4 v212, v[52:55], s[76:77] offset:256
	s_waitcnt lgkmcnt(0)
	global_store_dwordx4 v214, v[202:205], s[74:75] offset:512
	global_store_dwordx4 v215, v[206:209], s[74:75] offset:512
	s_waitcnt vmcnt(26)
	s_add_u32 s74, s62, 0x90000
	s_addc_u32 s75, s63, 0
	s_add_u32 s76, s88, 0x48000
	s_addc_u32 s77, s89, 0
	v_pk_fma_f32 v[128:129], v[44:45], v[60:61], v[128:129]
	v_pk_fma_f32 v[130:131], v[46:47], v[62:63], v[130:131]
	v_pk_fma_f32 v[124:125], v[40:41], v[64:65], v[124:125]
	v_pk_fma_f32 v[126:127], v[42:43], v[66:67], v[126:127]
	ds_write_b128 v236, v[128:131]
	ds_write_b128 v236, v[124:127] offset:64
	v_fmac_f32_e32 v229, v128, v128
	v_fmac_f32_e32 v229, v129, v129
	v_fmac_f32_e32 v229, v130, v130
	v_fmac_f32_e32 v229, v131, v131
	v_pk_mul_f32 v[44:45], v[148:149], v[128:129]
	v_pk_mul_f32 v[46:47], v[150:151], v[130:131]
	v_fmac_f32_e32 v229, v124, v124
	v_fmac_f32_e32 v229, v125, v125
	v_fmac_f32_e32 v229, v126, v126
	v_fmac_f32_e32 v229, v127, v127
	v_pk_mul_f32 v[40:41], v[152:153], v[124:125]
	v_pk_mul_f32 v[42:43], v[154:155], v[126:127]
	ds_read_b128 v[128:131], v237
	ds_read_b128 v[124:127], v237 offset:1024
	v_cvt_pk_bf16_f32 v44, v44, v45
	v_cvt_pk_bf16_f32 v45, v46, v47
	v_cvt_pk_bf16_f32 v46, v40, v41
	v_cvt_pk_bf16_f32 v47, v42, v43
	s_nop 1
	v_permlane16_swap_b32 v44, v46
	v_permlane16_swap_b32 v45, v47
	global_store_dwordx4 v212, v[44:47], s[76:77] offset:0
	s_waitcnt lgkmcnt(0)
	global_store_dwordx4 v214, v[128:131], s[74:75] offset:0
	global_store_dwordx4 v215, v[124:127], s[74:75] offset:0
	v_pk_fma_f32 v[120:121], v[36:37], v[68:69], v[120:121]
	v_pk_fma_f32 v[122:123], v[38:39], v[70:71], v[122:123]
	v_pk_fma_f32 v[116:117], v[32:33], v[72:73], v[116:117]
	v_pk_fma_f32 v[118:119], v[34:35], v[74:75], v[118:119]
	ds_write_b128 v236, v[120:123]
	ds_write_b128 v236, v[116:119] offset:64
	v_fmac_f32_e32 v229, v120, v120
	v_fmac_f32_e32 v229, v121, v121
	v_fmac_f32_e32 v229, v122, v122
	v_fmac_f32_e32 v229, v123, v123
	v_pk_mul_f32 v[36:37], v[156:157], v[120:121]
	v_pk_mul_f32 v[38:39], v[158:159], v[122:123]
	v_fmac_f32_e32 v229, v116, v116
	v_fmac_f32_e32 v229, v117, v117
	v_fmac_f32_e32 v229, v118, v118
	v_fmac_f32_e32 v229, v119, v119
	v_pk_mul_f32 v[32:33], v[160:161], v[116:117]
	v_pk_mul_f32 v[34:35], v[162:163], v[118:119]
	ds_read_b128 v[120:123], v237
	ds_read_b128 v[116:119], v237 offset:1024
	v_cvt_pk_bf16_f32 v36, v36, v37
	v_cvt_pk_bf16_f32 v37, v38, v39
	v_cvt_pk_bf16_f32 v38, v32, v33
	v_cvt_pk_bf16_f32 v39, v34, v35
	s_nop 1
	v_permlane16_swap_b32 v36, v38
	v_permlane16_swap_b32 v37, v39
	global_store_dwordx4 v212, v[36:39], s[76:77] offset:256
	s_waitcnt lgkmcnt(0)
	global_store_dwordx4 v214, v[120:123], s[74:75] offset:512
	global_store_dwordx4 v215, v[116:119], s[74:75] offset:512
	s_waitcnt vmcnt(22)
	s_add_u32 s74, s62, 0xa0000
	s_addc_u32 s75, s63, 0
	s_add_u32 s76, s88, 0x50000
	s_addc_u32 s77, s89, 0
	v_pk_fma_f32 v[164:165], v[28:29], v[60:61], v[164:165]
	v_pk_fma_f32 v[166:167], v[30:31], v[62:63], v[166:167]
	v_pk_fma_f32 v[168:169], v[24:25], v[64:65], v[168:169]
	v_pk_fma_f32 v[170:171], v[26:27], v[66:67], v[170:171]
	ds_write_b128 v236, v[164:167]
	ds_write_b128 v236, v[168:171] offset:64
	v_fmac_f32_e32 v234, v164, v164
	v_fmac_f32_e32 v234, v165, v165
	v_fmac_f32_e32 v234, v166, v166
	v_fmac_f32_e32 v234, v167, v167
	v_pk_mul_f32 v[28:29], v[148:149], v[164:165]
	v_pk_mul_f32 v[30:31], v[150:151], v[166:167]
	v_fmac_f32_e32 v234, v168, v168
	v_fmac_f32_e32 v234, v169, v169
	v_fmac_f32_e32 v234, v170, v170
	v_fmac_f32_e32 v234, v171, v171
	v_pk_mul_f32 v[24:25], v[152:153], v[168:169]
	v_pk_mul_f32 v[26:27], v[154:155], v[170:171]
	ds_read_b128 v[164:167], v237
	ds_read_b128 v[168:171], v237 offset:1024
	v_cvt_pk_bf16_f32 v28, v28, v29
	v_cvt_pk_bf16_f32 v29, v30, v31
	v_cvt_pk_bf16_f32 v30, v24, v25
	v_cvt_pk_bf16_f32 v31, v26, v27
	s_nop 1
	v_permlane16_swap_b32 v28, v30
	v_permlane16_swap_b32 v29, v31
	global_store_dwordx4 v212, v[28:31], s[76:77] offset:0
	s_waitcnt lgkmcnt(0)
	global_store_dwordx4 v214, v[164:167], s[74:75] offset:0
	global_store_dwordx4 v215, v[168:171], s[74:75] offset:0
	v_pk_fma_f32 v[172:173], v[20:21], v[68:69], v[172:173]
	v_pk_fma_f32 v[174:175], v[22:23], v[70:71], v[174:175]
	v_pk_fma_f32 v[176:177], v[16:17], v[72:73], v[176:177]
	v_pk_fma_f32 v[178:179], v[18:19], v[74:75], v[178:179]
	ds_write_b128 v236, v[172:175]
	ds_write_b128 v236, v[176:179] offset:64
	v_fmac_f32_e32 v234, v172, v172
	v_fmac_f32_e32 v234, v173, v173
	v_fmac_f32_e32 v234, v174, v174
	v_fmac_f32_e32 v234, v175, v175
	v_pk_mul_f32 v[20:21], v[156:157], v[172:173]
	v_pk_mul_f32 v[22:23], v[158:159], v[174:175]
	v_fmac_f32_e32 v234, v176, v176
	v_fmac_f32_e32 v234, v177, v177
	v_fmac_f32_e32 v234, v178, v178
	v_fmac_f32_e32 v234, v179, v179
	v_pk_mul_f32 v[16:17], v[160:161], v[176:177]
	v_pk_mul_f32 v[18:19], v[162:163], v[178:179]
	ds_read_b128 v[172:175], v237
	ds_read_b128 v[176:179], v237 offset:1024
	v_cvt_pk_bf16_f32 v20, v20, v21
	v_cvt_pk_bf16_f32 v21, v22, v23
	v_cvt_pk_bf16_f32 v22, v16, v17
	v_cvt_pk_bf16_f32 v23, v18, v19
	s_nop 1
	v_permlane16_swap_b32 v20, v22
	v_permlane16_swap_b32 v21, v23
	global_store_dwordx4 v212, v[20:23], s[76:77] offset:256
	s_waitcnt lgkmcnt(0)
	global_store_dwordx4 v214, v[172:175], s[74:75] offset:512
	global_store_dwordx4 v215, v[176:179], s[74:75] offset:512
	s_waitcnt vmcnt(24)
	s_add_u32 s74, s62, 0xb0000
	s_addc_u32 s75, s63, 0
	s_add_u32 s76, s88, 0x58000
	s_addc_u32 s77, s89, 0
	v_pk_fma_f32 v[112:113], v[12:13], v[60:61], v[112:113]
	v_pk_fma_f32 v[114:115], v[14:15], v[62:63], v[114:115]
	v_pk_fma_f32 v[108:109], v[8:9], v[64:65], v[108:109]
	v_pk_fma_f32 v[110:111], v[10:11], v[66:67], v[110:111]
	ds_write_b128 v236, v[112:115]
	ds_write_b128 v236, v[108:111] offset:64
	v_fmac_f32_e32 v235, v112, v112
	v_fmac_f32_e32 v235, v113, v113
	v_fmac_f32_e32 v235, v114, v114
	v_fmac_f32_e32 v235, v115, v115
	v_pk_mul_f32 v[12:13], v[148:149], v[112:113]
	v_pk_mul_f32 v[14:15], v[150:151], v[114:115]
	v_fmac_f32_e32 v235, v108, v108
	v_fmac_f32_e32 v235, v109, v109
	v_fmac_f32_e32 v235, v110, v110
	v_fmac_f32_e32 v235, v111, v111
	v_pk_mul_f32 v[8:9], v[152:153], v[108:109]
	v_pk_mul_f32 v[10:11], v[154:155], v[110:111]
	ds_read_b128 v[112:115], v237
	ds_read_b128 v[108:111], v237 offset:1024
	v_cvt_pk_bf16_f32 v12, v12, v13
	v_cvt_pk_bf16_f32 v13, v14, v15
	v_cvt_pk_bf16_f32 v14, v8, v9
	v_cvt_pk_bf16_f32 v15, v10, v11
	s_nop 1
	v_permlane16_swap_b32 v12, v14
	v_permlane16_swap_b32 v13, v15
	global_store_dwordx4 v212, v[12:15], s[76:77] offset:0
	s_waitcnt lgkmcnt(0)
	global_store_dwordx4 v214, v[112:115], s[74:75] offset:0
	global_store_dwordx4 v215, v[108:111], s[74:75] offset:0
	v_pk_fma_f32 v[104:105], v[4:5], v[68:69], v[104:105]
	v_pk_fma_f32 v[106:107], v[6:7], v[70:71], v[106:107]
	v_pk_fma_f32 v[100:101], v[0:1], v[72:73], v[100:101]
	v_pk_fma_f32 v[102:103], v[2:3], v[74:75], v[102:103]
	ds_write_b128 v236, v[104:107]
	ds_write_b128 v236, v[100:103] offset:64
	v_fmac_f32_e32 v235, v104, v104
	v_fmac_f32_e32 v235, v105, v105
	v_fmac_f32_e32 v235, v106, v106
	v_fmac_f32_e32 v235, v107, v107
	v_pk_mul_f32 v[4:5], v[156:157], v[104:105]
	v_pk_mul_f32 v[6:7], v[158:159], v[106:107]
	v_fmac_f32_e32 v235, v100, v100
	v_fmac_f32_e32 v235, v101, v101
	v_fmac_f32_e32 v235, v102, v102
	v_fmac_f32_e32 v235, v103, v103
	v_pk_mul_f32 v[0:1], v[160:161], v[100:101]
	v_pk_mul_f32 v[2:3], v[162:163], v[102:103]
	ds_read_b128 v[104:107], v237
	ds_read_b128 v[100:103], v237 offset:1024
	v_cvt_pk_bf16_f32 v4, v4, v5
	v_cvt_pk_bf16_f32 v5, v6, v7
	v_cvt_pk_bf16_f32 v6, v0, v1
	v_cvt_pk_bf16_f32 v7, v2, v3
	s_nop 1
	v_permlane16_swap_b32 v4, v6
	v_permlane16_swap_b32 v5, v7
	global_store_dwordx4 v212, v[4:7], s[76:77] offset:256
	s_waitcnt lgkmcnt(0)
	global_store_dwordx4 v214, v[104:107], s[74:75] offset:512
	global_store_dwordx4 v215, v[100:103], s[74:75] offset:512
	v_lshlrev_b32_e32 v214, 2, v231
	v_lshlrev_b32_e32 v215, 2, v232
	ds_bpermute_b32 v164, v214, v216
	ds_bpermute_b32 v165, v214, v217
	ds_bpermute_b32 v166, v214, v218
	ds_bpermute_b32 v167, v214, v219
	ds_bpermute_b32 v168, v214, v228
	ds_bpermute_b32 v169, v214, v229
	ds_bpermute_b32 v170, v214, v234
	ds_bpermute_b32 v171, v214, v235
	s_waitcnt lgkmcnt(0)
	v_add_f32_e32 v216, v216, v164
	v_add_f32_e32 v217, v217, v165
	v_add_f32_e32 v218, v218, v166
	v_add_f32_e32 v219, v219, v167
	v_add_f32_e32 v228, v228, v168
	v_add_f32_e32 v229, v229, v169
	v_add_f32_e32 v234, v234, v170
	v_add_f32_e32 v235, v235, v171
	ds_bpermute_b32 v164, v215, v216
	ds_bpermute_b32 v165, v215, v217
	ds_bpermute_b32 v166, v215, v218
	ds_bpermute_b32 v167, v215, v219
	ds_bpermute_b32 v168, v215, v228
	ds_bpermute_b32 v169, v215, v229
	ds_bpermute_b32 v170, v215, v234
	ds_bpermute_b32 v171, v215, v235
	s_waitcnt lgkmcnt(0)
	v_add_f32_e32 v216, v216, v164
	v_add_f32_e32 v217, v217, v165
	v_add_f32_e32 v218, v218, v166
	v_add_f32_e32 v219, v219, v167
	v_add_f32_e32 v228, v228, v168
	v_add_f32_e32 v229, v229, v169
	v_add_f32_e32 v234, v234, v170
	v_add_f32_e32 v235, v235, v171
	s_and_saveexec_b64 s[44:45], s[40:41]
	s_cbranch_execz .Lresid_noatom
	global_atomic_add_f32 v213, v216, s[6:7] offset:0
	global_atomic_add_f32 v213, v217, s[6:7] offset:64
	global_atomic_add_f32 v213, v218, s[6:7] offset:128
	global_atomic_add_f32 v213, v219, s[6:7] offset:192
	global_atomic_add_f32 v213, v228, s[6:7] offset:512
	global_atomic_add_f32 v213, v229, s[6:7] offset:576
	global_atomic_add_f32 v213, v234, s[6:7] offset:640
	global_atomic_add_f32 v213, v235, s[6:7] offset:704

.Lresid_nonorm:
	v_readlane_b32 s62, v252, 7
	v_readlane_b32 s63, v252, 8
	s_lshr_b32 s20, s56, 4
	s_mul_i32 s20, s20, 0x6000
	s_add_u32 s44, s66, s20
	s_addc_u32 s45, s12, 0
	s_add_u32 s46, s13, s20
	s_addc_u32 s47, s26, 0
	s_mov_b32 s60, s38
	s_mov_b32 s61, s95
	v_lshl_or_b32 v236, s57, 8, v246
	v_lshl_add_u32 v237, s56, 8, v244
	v_lshlrev_b32_e32 v210, 2, v236
	v_lshl_add_u32 v211, v237, 12, v210
	v_and_b32_e32 v212, 4, v246
	v_mul_u32_u24_e32 v212, 6, v212
	v_lshl_add_u32 v212, v236, 1, v212
	v_lshl_add_u32 v212, v237, 11, v212
	v_lshlrev_b32_e32 v213, 2, v237
	v_lshlrev_b32_e32 v214, 2, v231
	v_lshlrev_b32_e32 v215, 2, v232
	v_and_b32_e32 v228, 63, v186
	v_lshrrev_b32_e32 v229, 6, v186
	v_lshlrev_b32_e32 v229, 11, v229
	v_add_u32_e32 v229, 0x20100, v229
	v_lshl_add_u32 v237, v228, 4, v229
	v_and_b32_e32 v236, 15, v244
	v_lshl_add_u32 v236, v236, 7, v229
	v_and_b32_e32 v229, 12, v246
	v_lshl_add_u32 v236, v229, 2, v236
	v_lshrrev_b32_e32 v214, 3, v228
	v_and_b32_e32 v229, 64, v244
	v_add_u32_e32 v214, v214, v229
	v_lshl_add_u32 v214, s56, 8, v214
	v_and_b32_e32 v228, 7, v228
	v_lshlrev_b32_e32 v228, 2, v228
	v_and_b32_e32 v229, 0x60, v246
	v_add_u32_e32 v228, v228, v229
	v_lshl_add_u32 v228, s57, 8, v228
	v_lshlrev_b32_e32 v228, 2, v228
	v_lshl_add_u32 v214, v214, 12, v228
	v_add_u32_e32 v215, 0x8000, v214
	global_load_dwordx4 v[60:63], v210, s[44:45] offset:0
	global_load_dwordx4 v[64:67], v210, s[44:45] offset:64
	global_load_dwordx4 v[68:71], v210, s[44:45] offset:512
	global_load_dwordx4 v[72:75], v210, s[44:45] offset:576
	s_mov_b32 s72, s60
	s_mov_b32 s73, s61
	global_load_dwordx4 v[164:167], v211, s[72:73] offset:0
	global_load_dwordx4 v[168:171], v211, s[72:73] offset:64
	global_load_dwordx4 v[172:175], v211, s[72:73] offset:512
	global_load_dwordx4 v[176:179], v211, s[72:73] offset:576
	s_add_u32 s72, s60, 0x10000
	s_addc_u32 s73, s61, 0
	global_load_dwordx4 v[194:197], v211, s[72:73] offset:0
	global_load_dwordx4 v[198:201], v211, s[72:73] offset:64
	global_load_dwordx4 v[202:205], v211, s[72:73] offset:512
	global_load_dwordx4 v[206:209], v211, s[72:73] offset:576
	s_waitcnt vmcnt(4)
	s_mov_b32 s74, s62
	s_mov_b32 s75, s63
	v_pk_fma_f32 v[164:165], v[144:145], v[60:61], v[164:165]
	v_pk_fma_f32 v[166:167], v[146:147], v[62:63], v[166:167]
	v_pk_fma_f32 v[168:169], v[140:141], v[64:65], v[168:169]
	v_pk_fma_f32 v[170:171], v[142:143], v[66:67], v[170:171]
	ds_write_b128 v236, v[164:167]
	ds_write_b128 v236, v[168:171] offset:64
	ds_read_b128 v[164:167], v237
	ds_read_b128 v[168:171], v237 offset:1024
	s_waitcnt lgkmcnt(0)
	global_store_dwordx4 v214, v[164:167], s[74:75] offset:0
	global_store_dwordx4 v215, v[168:171], s[74:75] offset:0
	v_pk_fma_f32 v[172:173], v[136:137], v[68:69], v[172:173]
	v_pk_fma_f32 v[174:175], v[138:139], v[70:71], v[174:175]
	v_pk_fma_f32 v[176:177], v[132:133], v[72:73], v[176:177]
	v_pk_fma_f32 v[178:179], v[134:135], v[74:75], v[178:179]
	ds_write_b128 v236, v[172:175]
	ds_write_b128 v236, v[176:179] offset:64
	ds_read_b128 v[172:175], v237
	ds_read_b128 v[176:179], v237 offset:1024
	s_waitcnt lgkmcnt(0)
	global_store_dwordx4 v214, v[172:175], s[74:75] offset:512
	global_store_dwordx4 v215, v[176:179], s[74:75] offset:512
	s_add_u32 s72, s60, 0x20000
	s_addc_u32 s73, s61, 0
	global_load_dwordx4 v[164:167], v211, s[72:73] offset:0
	global_load_dwordx4 v[168:171], v211, s[72:73] offset:64
	global_load_dwordx4 v[172:175], v211, s[72:73] offset:512
	global_load_dwordx4 v[176:179], v211, s[72:73] offset:576
	s_add_u32 s72, s60, 0x30000
	s_addc_u32 s73, s61, 0
	global_load_dwordx4 v[144:147], v211, s[72:73] offset:0
	global_load_dwordx4 v[140:143], v211, s[72:73] offset:64
	global_load_dwordx4 v[136:139], v211, s[72:73] offset:512
	global_load_dwordx4 v[132:135], v211, s[72:73] offset:576
	s_waitcnt vmcnt(12)
	s_add_u32 s74, s62, 0x10000
	s_addc_u32 s75, s63, 0
	v_pk_fma_f32 v[194:195], v[128:129], v[60:61], v[194:195]
	v_pk_fma_f32 v[196:197], v[130:131], v[62:63], v[196:197]
	v_pk_fma_f32 v[198:199], v[124:125], v[64:65], v[198:199]
	v_pk_fma_f32 v[200:201], v[126:127], v[66:67], v[200:201]
	ds_write_b128 v236, v[194:197]
	ds_write_b128 v236, v[198:201] offset:64
	ds_read_b128 v[194:197], v237
	ds_read_b128 v[198:201], v237 offset:1024
	s_waitcnt lgkmcnt(0)
	global_store_dwordx4 v214, v[194:197], s[74:75] offset:0
	global_store_dwordx4 v215, v[198:201], s[74:75] offset:0
	v_pk_fma_f32 v[202:203], v[120:121], v[68:69], v[202:203]
	v_pk_fma_f32 v[204:205], v[122:123], v[70:71], v[204:205]
	v_pk_fma_f32 v[206:207], v[116:117], v[72:73], v[206:207]
	v_pk_fma_f32 v[208:209], v[118:119], v[74:75], v[208:209]
	ds_write_b128 v236, v[202:205]
	ds_write_b128 v236, v[206:209] offset:64
	ds_read_b128 v[202:205], v237
	ds_read_b128 v[206:209], v237 offset:1024
	s_waitcnt lgkmcnt(0)
	global_store_dwordx4 v214, v[202:205], s[74:75] offset:512
	global_store_dwordx4 v215, v[206:209], s[74:75] offset:512
	s_add_u32 s72, s60, 0x80000
	s_addc_u32 s73, s61, 0
	global_load_dwordx4 v[194:197], v211, s[72:73] offset:0
	global_load_dwordx4 v[198:201], v211, s[72:73] offset:64
	global_load_dwordx4 v[202:205], v211, s[72:73] offset:512
	global_load_dwordx4 v[206:209], v211, s[72:73] offset:576
	s_add_u32 s72, s60, 0x90000
	s_addc_u32 s73, s61, 0
	global_load_dwordx4 v[128:131], v211, s[72:73] offset:0
	global_load_dwordx4 v[124:127], v211, s[72:73] offset:64
	global_load_dwordx4 v[120:123], v211, s[72:73] offset:512
	global_load_dwordx4 v[116:119], v211, s[72:73] offset:576
	s_waitcnt vmcnt(16)
	s_add_u32 s74, s62, 0x20000
	s_addc_u32 s75, s63, 0
	v_pk_fma_f32 v[164:165], v[112:113], v[60:61], v[164:165]
	v_pk_fma_f32 v[166:167], v[114:115], v[62:63], v[166:167]
	v_pk_fma_f32 v[168:169], v[108:109], v[64:65], v[168:169]
	v_pk_fma_f32 v[170:171], v[110:111], v[66:67], v[170:171]
	ds_write_b128 v236, v[164:167]
	ds_write_b128 v236, v[168:171] offset:64
	ds_read_b128 v[164:167], v237
	ds_read_b128 v[168:171], v237 offset:1024
	s_waitcnt lgkmcnt(0)
	global_store_dwordx4 v214, v[164:167], s[74:75] offset:0
	global_store_dwordx4 v215, v[168:171], s[74:75] offset:0
	v_pk_fma_f32 v[172:173], v[104:105], v[68:69], v[172:173]
	v_pk_fma_f32 v[174:175], v[106:107], v[70:71], v[174:175]
	v_pk_fma_f32 v[176:177], v[100:101], v[72:73], v[176:177]
	v_pk_fma_f32 v[178:179], v[102:103], v[74:75], v[178:179]
	ds_write_b128 v236, v[172:175]
	ds_write_b128 v236, v[176:179] offset:64
	ds_read_b128 v[172:175], v237
	ds_read_b128 v[176:179], v237 offset:1024
	s_waitcnt lgkmcnt(0)
	global_store_dwordx4 v214, v[172:175], s[74:75] offset:512
	global_store_dwordx4 v215, v[176:179], s[74:75] offset:512
	s_add_u32 s72, s60, 0xa0000
	s_addc_u32 s73, s61, 0
	global_load_dwordx4 v[164:167], v211, s[72:73] offset:0
	global_load_dwordx4 v[168:171], v211, s[72:73] offset:64
	global_load_dwordx4 v[172:175], v211, s[72:73] offset:512
	global_load_dwordx4 v[176:179], v211, s[72:73] offset:576
	s_add_u32 s72, s60, 0xb0000
	s_addc_u32 s73, s61, 0
	global_load_dwordx4 v[112:115], v211, s[72:73] offset:0
	global_load_dwordx4 v[108:111], v211, s[72:73] offset:64
	global_load_dwordx4 v[104:107], v211, s[72:73] offset:512
	global_load_dwordx4 v[100:103], v211, s[72:73] offset:576
	s_waitcnt vmcnt(24)
	s_add_u32 s74, s62, 0x30000
	s_addc_u32 s75, s63, 0
	v_pk_fma_f32 v[144:145], v[92:93], v[60:61], v[144:145]
	v_pk_fma_f32 v[146:147], v[94:95], v[62:63], v[146:147]
	v_pk_fma_f32 v[140:141], v[88:89], v[64:65], v[140:141]
	v_pk_fma_f32 v[142:143], v[90:91], v[66:67], v[142:143]
	ds_write_b128 v236, v[144:147]
	ds_write_b128 v236, v[140:143] offset:64
	ds_read_b128 v[144:147], v237
	ds_read_b128 v[140:143], v237 offset:1024
	s_waitcnt lgkmcnt(0)
	global_store_dwordx4 v214, v[144:147], s[74:75] offset:0
	global_store_dwordx4 v215, v[140:143], s[74:75] offset:0
	v_pk_fma_f32 v[136:137], v[84:85], v[68:69], v[136:137]
	v_pk_fma_f32 v[138:139], v[86:87], v[70:71], v[138:139]
	v_pk_fma_f32 v[132:133], v[80:81], v[72:73], v[132:133]
	v_pk_fma_f32 v[134:135], v[82:83], v[74:75], v[134:135]
	ds_write_b128 v236, v[136:139]
	ds_write_b128 v236, v[132:135] offset:64
	ds_read_b128 v[136:139], v237
	ds_read_b128 v[132:135], v237 offset:1024
	s_waitcnt lgkmcnt(0)
	global_store_dwordx4 v214, v[136:139], s[74:75] offset:512
	global_store_dwordx4 v215, v[132:135], s[74:75] offset:512
	s_waitcnt vmcnt(20)
	s_add_u32 s74, s62, 0x80000
	s_addc_u32 s75, s63, 0
	v_pk_fma_f32 v[194:195], v[76:77], v[60:61], v[194:195]
	v_pk_fma_f32 v[196:197], v[78:79], v[62:63], v[196:197]
	v_pk_fma_f32 v[198:199], v[56:57], v[64:65], v[198:199]
	v_pk_fma_f32 v[200:201], v[58:59], v[66:67], v[200:201]
	ds_write_b128 v236, v[194:197]
	ds_write_b128 v236, v[198:201] offset:64
	ds_read_b128 v[194:197], v237
	ds_read_b128 v[198:201], v237 offset:1024
	s_waitcnt lgkmcnt(0)
	global_store_dwordx4 v214, v[194:197], s[74:75] offset:0
	global_store_dwordx4 v215, v[198:201], s[74:75] offset:0
	v_pk_fma_f32 v[202:203], v[52:53], v[68:69], v[202:203]
	v_pk_fma_f32 v[204:205], v[54:55], v[70:71], v[204:205]
	v_pk_fma_f32 v[206:207], v[48:49], v[72:73], v[206:207]
	v_pk_fma_f32 v[208:209], v[50:51], v[74:75], v[208:209]
	ds_write_b128 v236, v[202:205]
	ds_write_b128 v236, v[206:209] offset:64
	ds_read_b128 v[202:205], v237
	ds_read_b128 v[206:209], v237 offset:1024
	s_waitcnt lgkmcnt(0)
	global_store_dwordx4 v214, v[202:205], s[74:75] offset:512
	global_store_dwordx4 v215, v[206:209], s[74:75] offset:512
	s_waitcnt vmcnt(20)
	s_add_u32 s74, s62, 0x90000
	s_addc_u32 s75, s63, 0
	v_pk_fma_f32 v[128:129], v[44:45], v[60:61], v[128:129]
	v_pk_fma_f32 v[130:131], v[46:47], v[62:63], v[130:131]
	v_pk_fma_f32 v[124:125], v[40:41], v[64:65], v[124:125]
	v_pk_fma_f32 v[126:127], v[42:43], v[66:67], v[126:127]
	ds_write_b128 v236, v[128:131]
	ds_write_b128 v236, v[124:127] offset:64
	ds_read_b128 v[128:131], v237
	ds_read_b128 v[124:127], v237 offset:1024
	s_waitcnt lgkmcnt(0)
	global_store_dwordx4 v214, v[128:131], s[74:75] offset:0
	global_store_dwordx4 v215, v[124:127], s[74:75] offset:0
	v_pk_fma_f32 v[120:121], v[36:37], v[68:69], v[120:121]
	v_pk_fma_f32 v[122:123], v[38:39], v[70:71], v[122:123]
	v_pk_fma_f32 v[116:117], v[32:33], v[72:73], v[116:117]
	v_pk_fma_f32 v[118:119], v[34:35], v[74:75], v[118:119]
	ds_write_b128 v236, v[120:123]
	ds_write_b128 v236, v[116:119] offset:64
	ds_read_b128 v[120:123], v237
	ds_read_b128 v[116:119], v237 offset:1024
	s_waitcnt lgkmcnt(0)
	global_store_dwordx4 v214, v[120:123], s[74:75] offset:512
	global_store_dwordx4 v215, v[116:119], s[74:75] offset:512
	s_waitcnt vmcnt(16)
	s_add_u32 s74, s62, 0xa0000
	s_addc_u32 s75, s63, 0
	v_pk_fma_f32 v[164:165], v[28:29], v[60:61], v[164:165]
	v_pk_fma_f32 v[166:167], v[30:31], v[62:63], v[166:167]
	v_pk_fma_f32 v[168:169], v[24:25], v[64:65], v[168:169]
	v_pk_fma_f32 v[170:171], v[26:27], v[66:67], v[170:171]
	ds_write_b128 v236, v[164:167]
	ds_write_b128 v236, v[168:171] offset:64
	ds_read_b128 v[164:167], v237
	ds_read_b128 v[168:171], v237 offset:1024
	s_waitcnt lgkmcnt(0)
	global_store_dwordx4 v214, v[164:167], s[74:75] offset:0
	global_store_dwordx4 v215, v[168:171], s[74:75] offset:0
	v_pk_fma_f32 v[172:173], v[20:21], v[68:69], v[172:173]
	v_pk_fma_f32 v[174:175], v[22:23], v[70:71], v[174:175]
	v_pk_fma_f32 v[176:177], v[16:17], v[72:73], v[176:177]
	v_pk_fma_f32 v[178:179], v[18:19], v[74:75], v[178:179]
	ds_write_b128 v236, v[172:175]
	ds_write_b128 v236, v[176:179] offset:64
	ds_read_b128 v[172:175], v237
	ds_read_b128 v[176:179], v237 offset:1024
	s_waitcnt lgkmcnt(0)
	global_store_dwordx4 v214, v[172:175], s[74:75] offset:512
	global_store_dwordx4 v215, v[176:179], s[74:75] offset:512
	s_waitcnt vmcnt(16)
	s_add_u32 s74, s62, 0xb0000
	s_addc_u32 s75, s63, 0
	v_pk_fma_f32 v[112:113], v[12:13], v[60:61], v[112:113]
	v_pk_fma_f32 v[114:115], v[14:15], v[62:63], v[114:115]
	v_pk_fma_f32 v[108:109], v[8:9], v[64:65], v[108:109]
	v_pk_fma_f32 v[110:111], v[10:11], v[66:67], v[110:111]
	ds_write_b128 v236, v[112:115]
	ds_write_b128 v236, v[108:111] offset:64
	ds_read_b128 v[112:115], v237
	ds_read_b128 v[108:111], v237 offset:1024
	s_waitcnt lgkmcnt(0)
	global_store_dwordx4 v214, v[112:115], s[74:75] offset:0
	global_store_dwordx4 v215, v[108:111], s[74:75] offset:0
	v_pk_fma_f32 v[104:105], v[4:5], v[68:69], v[104:105]
	v_pk_fma_f32 v[106:107], v[6:7], v[70:71], v[106:107]
	v_pk_fma_f32 v[100:101], v[0:1], v[72:73], v[100:101]
	v_pk_fma_f32 v[102:103], v[2:3], v[74:75], v[102:103]
	ds_write_b128 v236, v[104:107]
	ds_write_b128 v236, v[100:103] offset:64
	ds_read_b128 v[104:107], v237
	ds_read_b128 v[100:103], v237 offset:1024
	s_waitcnt lgkmcnt(0)
	global_store_dwordx4 v214, v[104:107], s[74:75] offset:512
	global_store_dwordx4 v215, v[100:103], s[74:75] offset:512
	s_branch .Lresid_done
